# baseline (speedup 1.0000x reference)
; template <bool FINAL, bool XB, bool MI = false> ...
;     ...
;             if (!lat && part) {
;                 const size_t ro = (size_t)(row - MLAT) * DM;
; #pragma unroll
;                 for (int j = 0; j < 8; ++j) { const int c = 4 * F.lane + 256 * j; const f32x4 g4 = *(const f32x4*)(pgate + c);
;                     const f32x4 p = (*(const f32x4*)(part + ro + c) + *(const f32x4*)(part + (size_t)MCTX * DM + ro + c)) + (*(const f32x4*)(part + (size_t)2 * MCTX * DM + ro + c) + *(const f32x4*)(part + (size_t)3 * MCTX * DM + ro + c));
;                     v[u][j] = v[u][j] + g4 * p; *(f32x4*)(ctx_wb + ro + c) = v[u][j]; }
.LBB0_949:
	s_cmpk_lt_i32 s25, 0x4000
	v_lshlrev_b32_e32 v102, 2, v100
	s_cbranch_scc1 .LBB0_951
	s_lshl_b64 s[0:1], s[14:15], 13
	s_add_u32 s44, s80, s0
	s_addc_u32 s45, s81, s1
	s_add_u32 s52, s63, s0
	s_addc_u32 s53, s64, s1
	s_add_u32 s38, s65, s0
	s_addc_u32 s39, s68, s1
	s_add_u32 s40, s69, s0
	s_addc_u32 s41, s70, s1
	s_add_u32 s0, s4, s0
	s_addc_u32 s1, s5, s1
	global_load_dwordx4 v[96:99], v[138:139], off
	global_load_dwordx4 v[180:183], v102, s[44:45]
	global_load_dwordx4 v[184:187], v102, s[52:53]
	global_load_dwordx4 v[214:217], v102, s[38:39]
	global_load_dwordx4 v[218:221], v102, s[40:41]
	global_load_dwordx4 v[222:225], v[140:141], off
	global_load_dwordx4 v[226:229], v102, s[44:45] offset:1024
	global_load_dwordx4 v[230:233], v102, s[52:53] offset:1024
	global_load_dwordx4 v[234:237], v102, s[38:39] offset:1024
	global_load_dwordx4 v[238:241], v102, s[40:41] offset:1024
	s_waitcnt vmcnt(0)
	v_pk_add_f32 v[188:189], v[182:183], v[186:187]
	v_pk_add_f32 v[190:191], v[180:181], v[184:185]
	v_pk_add_f32 v[216:217], v[216:217], v[220:221]
	v_pk_add_f32 v[214:215], v[214:215], v[218:219]
	v_pk_add_f32 v[216:217], v[188:189], v[216:217]
	v_pk_add_f32 v[214:215], v[190:191], v[214:215]
	v_pk_fma_f32 v[94:95], v[98:99], v[216:217], v[94:95]
	v_pk_fma_f32 v[92:93], v[96:97], v[214:215], v[92:93]
	global_store_dwordx4 v102, v[92:95], s[0:1]
	v_pk_add_f32 v[188:189], v[228:229], v[232:233]
	v_pk_add_f32 v[190:191], v[226:227], v[230:231]
	v_pk_add_f32 v[236:237], v[236:237], v[240:241]
	v_pk_add_f32 v[234:235], v[234:235], v[238:239]
	v_pk_add_f32 v[236:237], v[188:189], v[236:237]
	v_pk_add_f32 v[234:235], v[190:191], v[234:235]
	v_pk_fma_f32 v[90:91], v[224:225], v[236:237], v[90:91]
	v_pk_fma_f32 v[88:89], v[222:223], v[234:235], v[88:89]
	global_store_dwordx4 v102, v[88:91], s[0:1] offset:1024
	global_load_dwordx4 v[96:99], v[142:143], off
	global_load_dwordx4 v[180:183], v102, s[44:45] offset:2048
	global_load_dwordx4 v[184:187], v102, s[52:53] offset:2048
	global_load_dwordx4 v[214:217], v102, s[38:39] offset:2048
	global_load_dwordx4 v[218:221], v102, s[40:41] offset:2048
	global_load_dwordx4 v[222:225], v[144:145], off
	global_load_dwordx4 v[226:229], v102, s[44:45] offset:3072
	global_load_dwordx4 v[230:233], v102, s[52:53] offset:3072
	global_load_dwordx4 v[234:237], v102, s[38:39] offset:3072
	global_load_dwordx4 v[238:241], v102, s[40:41] offset:3072
	s_waitcnt vmcnt(0)
	v_pk_add_f32 v[188:189], v[182:183], v[186:187]
	v_pk_add_f32 v[190:191], v[180:181], v[184:185]
	v_pk_add_f32 v[216:217], v[216:217], v[220:221]
	v_pk_add_f32 v[214:215], v[214:215], v[218:219]
	v_pk_add_f32 v[216:217], v[188:189], v[216:217]
	v_pk_add_f32 v[214:215], v[190:191], v[214:215]
	v_pk_fma_f32 v[86:87], v[98:99], v[216:217], v[86:87]
	v_pk_fma_f32 v[84:85], v[96:97], v[214:215], v[84:85]
	global_store_dwordx4 v102, v[84:87], s[0:1] offset:2048
	v_pk_add_f32 v[188:189], v[228:229], v[232:233]
	v_pk_add_f32 v[190:191], v[226:227], v[230:231]
	v_pk_add_f32 v[236:237], v[236:237], v[240:241]
	v_pk_add_f32 v[234:235], v[234:235], v[238:239]
	v_pk_add_f32 v[236:237], v[188:189], v[236:237]
	v_pk_add_f32 v[234:235], v[190:191], v[234:235]
	v_pk_fma_f32 v[82:83], v[224:225], v[236:237], v[82:83]
	v_pk_fma_f32 v[80:81], v[222:223], v[234:235], v[80:81]
	global_store_dwordx4 v102, v[80:83], s[0:1] offset:3072
	global_load_dwordx4 v[96:99], v[146:147], off
	global_load_dwordx4 v[180:183], v176, s[44:45]
	global_load_dwordx4 v[184:187], v176, s[52:53]
	global_load_dwordx4 v[214:217], v176, s[38:39]
	global_load_dwordx4 v[218:221], v176, s[40:41]
	global_load_dwordx4 v[222:225], v[148:149], off
	global_load_dwordx4 v[226:229], v177, s[44:45]
	global_load_dwordx4 v[230:233], v177, s[52:53]
	global_load_dwordx4 v[234:237], v177, s[38:39]
	global_load_dwordx4 v[238:241], v177, s[40:41]
	s_waitcnt vmcnt(0)
	v_pk_add_f32 v[188:189], v[182:183], v[186:187]
	v_pk_add_f32 v[190:191], v[180:181], v[184:185]
	v_pk_add_f32 v[216:217], v[216:217], v[220:221]
	v_pk_add_f32 v[214:215], v[214:215], v[218:219]
	v_pk_add_f32 v[216:217], v[188:189], v[216:217]
	v_pk_add_f32 v[214:215], v[190:191], v[214:215]
	v_pk_fma_f32 v[78:79], v[98:99], v[216:217], v[78:79]
	v_pk_fma_f32 v[76:77], v[96:97], v[214:215], v[76:77]
	global_store_dwordx4 v176, v[76:79], s[0:1]
	v_pk_add_f32 v[188:189], v[228:229], v[232:233]
	v_pk_add_f32 v[190:191], v[226:227], v[230:231]
	v_pk_add_f32 v[236:237], v[236:237], v[240:241]
	v_pk_add_f32 v[234:235], v[234:235], v[238:239]
	v_pk_add_f32 v[236:237], v[188:189], v[236:237]
	v_pk_add_f32 v[234:235], v[190:191], v[234:235]
	v_pk_fma_f32 v[74:75], v[224:225], v[236:237], v[74:75]
	v_pk_fma_f32 v[72:73], v[222:223], v[234:235], v[72:73]
	global_store_dwordx4 v177, v[72:75], s[0:1]
	global_load_dwordx4 v[96:99], v[150:151], off
	global_load_dwordx4 v[180:183], v178, s[44:45]
	global_load_dwordx4 v[184:187], v178, s[52:53]
	global_load_dwordx4 v[214:217], v178, s[38:39]
	global_load_dwordx4 v[218:221], v178, s[40:41]
	global_load_dwordx4 v[222:225], v[152:153], off
	global_load_dwordx4 v[226:229], v179, s[44:45]
	global_load_dwordx4 v[230:233], v179, s[52:53]
	global_load_dwordx4 v[234:237], v179, s[38:39]
	global_load_dwordx4 v[238:241], v179, s[40:41]
	s_waitcnt vmcnt(0)
	v_pk_add_f32 v[188:189], v[182:183], v[186:187]
	v_pk_add_f32 v[190:191], v[180:181], v[184:185]
	v_pk_add_f32 v[216:217], v[216:217], v[220:221]
	v_pk_add_f32 v[214:215], v[214:215], v[218:219]
	v_pk_add_f32 v[216:217], v[188:189], v[216:217]
	v_pk_add_f32 v[214:215], v[190:191], v[214:215]
	v_pk_fma_f32 v[70:71], v[98:99], v[216:217], v[70:71]
	v_pk_fma_f32 v[68:69], v[96:97], v[214:215], v[68:69]
	global_store_dwordx4 v178, v[68:71], s[0:1]
	v_pk_add_f32 v[188:189], v[228:229], v[232:233]
	v_pk_add_f32 v[190:191], v[226:227], v[230:231]
	v_pk_add_f32 v[236:237], v[236:237], v[240:241]
	v_pk_add_f32 v[234:235], v[234:235], v[238:239]
	v_pk_add_f32 v[236:237], v[188:189], v[236:237]
	v_pk_add_f32 v[234:235], v[190:191], v[234:235]
	v_pk_fma_f32 v[66:67], v[224:225], v[236:237], v[66:67]
	v_pk_fma_f32 v[64:65], v[222:223], v[234:235], v[64:65]
	global_store_dwordx4 v179, v[64:67], s[0:1]

; template <bool FINAL, bool XB, bool MI = false> ...
;     ...
;             if (!lat && part) {
;                 const size_t ro = (size_t)(row - MLAT) * DM;
; #pragma unroll
;                 for (int j = 0; j < 8; ++j) { const int c = 4 * F.lane + 256 * j; const f32x4 g4 = *(const f32x4*)(pgate + c);
;                     const f32x4 p = (*(const f32x4*)(part + ro + c) + *(const f32x4*)(part + (size_t)MCTX * DM + ro + c)) + (*(const f32x4*)(part + (size_t)2 * MCTX * DM + ro + c) + *(const f32x4*)(part + (size_t)3 * MCTX * DM + ro + c));
;                     v[u][j] = v[u][j] + g4 * p; *(f32x4*)(ctx_wb + ro + c) = v[u][j]; }
.LBB0_1192:
	s_cmpk_lt_i32 s25, 0x4000
	v_lshlrev_b32_e32 v102, 2, v100
	s_cbranch_scc1 .LBB0_1194
	s_lshl_b64 s[0:1], s[14:15], 13
	s_add_u32 s44, s80, s0
	s_addc_u32 s45, s81, s1
	s_add_u32 s52, s59, s0
	s_addc_u32 s53, s60, s1
	s_add_u32 s38, s61, s0
	s_addc_u32 s39, s62, s1
	s_add_u32 s40, s63, s0
	s_addc_u32 s41, s64, s1
	s_add_u32 s0, s4, s0
	s_addc_u32 s1, s5, s1
	global_load_dwordx4 v[96:99], v[138:139], off
	global_load_dwordx4 v[180:183], v102, s[44:45]
	global_load_dwordx4 v[184:187], v102, s[52:53]
	global_load_dwordx4 v[214:217], v102, s[38:39]
	global_load_dwordx4 v[218:221], v102, s[40:41]
	global_load_dwordx4 v[222:225], v[140:141], off
	global_load_dwordx4 v[226:229], v102, s[44:45] offset:1024
	global_load_dwordx4 v[230:233], v102, s[52:53] offset:1024
	global_load_dwordx4 v[234:237], v102, s[38:39] offset:1024
	global_load_dwordx4 v[238:241], v102, s[40:41] offset:1024
	s_waitcnt vmcnt(0)
	v_pk_add_f32 v[188:189], v[182:183], v[186:187]
	v_pk_add_f32 v[190:191], v[180:181], v[184:185]
	v_pk_add_f32 v[216:217], v[216:217], v[220:221]
	v_pk_add_f32 v[214:215], v[214:215], v[218:219]
	v_pk_add_f32 v[216:217], v[188:189], v[216:217]
	v_pk_add_f32 v[214:215], v[190:191], v[214:215]
	v_pk_fma_f32 v[94:95], v[98:99], v[216:217], v[94:95]
	v_pk_fma_f32 v[92:93], v[96:97], v[214:215], v[92:93]
	global_store_dwordx4 v102, v[92:95], s[0:1]
	v_pk_add_f32 v[188:189], v[228:229], v[232:233]
	v_pk_add_f32 v[190:191], v[226:227], v[230:231]
	v_pk_add_f32 v[236:237], v[236:237], v[240:241]
	v_pk_add_f32 v[234:235], v[234:235], v[238:239]
	v_pk_add_f32 v[236:237], v[188:189], v[236:237]
	v_pk_add_f32 v[234:235], v[190:191], v[234:235]
	v_pk_fma_f32 v[90:91], v[224:225], v[236:237], v[90:91]
	v_pk_fma_f32 v[88:89], v[222:223], v[234:235], v[88:89]
	global_store_dwordx4 v102, v[88:91], s[0:1] offset:1024
	global_load_dwordx4 v[96:99], v[142:143], off
	global_load_dwordx4 v[180:183], v102, s[44:45] offset:2048
	global_load_dwordx4 v[184:187], v102, s[52:53] offset:2048
	global_load_dwordx4 v[214:217], v102, s[38:39] offset:2048
	global_load_dwordx4 v[218:221], v102, s[40:41] offset:2048
	global_load_dwordx4 v[222:225], v[144:145], off
	global_load_dwordx4 v[226:229], v102, s[44:45] offset:3072
	global_load_dwordx4 v[230:233], v102, s[52:53] offset:3072
	global_load_dwordx4 v[234:237], v102, s[38:39] offset:3072
	global_load_dwordx4 v[238:241], v102, s[40:41] offset:3072
	s_waitcnt vmcnt(0)
	v_pk_add_f32 v[188:189], v[182:183], v[186:187]
	v_pk_add_f32 v[190:191], v[180:181], v[184:185]
	v_pk_add_f32 v[216:217], v[216:217], v[220:221]
	v_pk_add_f32 v[214:215], v[214:215], v[218:219]
	v_pk_add_f32 v[216:217], v[188:189], v[216:217]
	v_pk_add_f32 v[214:215], v[190:191], v[214:215]
	v_pk_fma_f32 v[86:87], v[98:99], v[216:217], v[86:87]
	v_pk_fma_f32 v[84:85], v[96:97], v[214:215], v[84:85]
	global_store_dwordx4 v102, v[84:87], s[0:1] offset:2048
	v_pk_add_f32 v[188:189], v[228:229], v[232:233]
	v_pk_add_f32 v[190:191], v[226:227], v[230:231]
	v_pk_add_f32 v[236:237], v[236:237], v[240:241]
	v_pk_add_f32 v[234:235], v[234:235], v[238:239]
	v_pk_add_f32 v[236:237], v[188:189], v[236:237]
	v_pk_add_f32 v[234:235], v[190:191], v[234:235]
	v_pk_fma_f32 v[82:83], v[224:225], v[236:237], v[82:83]
	v_pk_fma_f32 v[80:81], v[222:223], v[234:235], v[80:81]
	global_store_dwordx4 v102, v[80:83], s[0:1] offset:3072
	global_load_dwordx4 v[96:99], v[146:147], off
	global_load_dwordx4 v[180:183], v176, s[44:45]
	global_load_dwordx4 v[184:187], v176, s[52:53]
	global_load_dwordx4 v[214:217], v176, s[38:39]
	global_load_dwordx4 v[218:221], v176, s[40:41]
	global_load_dwordx4 v[222:225], v[148:149], off
	global_load_dwordx4 v[226:229], v177, s[44:45]
	global_load_dwordx4 v[230:233], v177, s[52:53]
	global_load_dwordx4 v[234:237], v177, s[38:39]
	global_load_dwordx4 v[238:241], v177, s[40:41]
	s_waitcnt vmcnt(0)
	v_pk_add_f32 v[188:189], v[182:183], v[186:187]
	v_pk_add_f32 v[190:191], v[180:181], v[184:185]
	v_pk_add_f32 v[216:217], v[216:217], v[220:221]
	v_pk_add_f32 v[214:215], v[214:215], v[218:219]
	v_pk_add_f32 v[216:217], v[188:189], v[216:217]
	v_pk_add_f32 v[214:215], v[190:191], v[214:215]
	v_pk_fma_f32 v[78:79], v[98:99], v[216:217], v[78:79]
	v_pk_fma_f32 v[76:77], v[96:97], v[214:215], v[76:77]
	global_store_dwordx4 v176, v[76:79], s[0:1]
	v_pk_add_f32 v[188:189], v[228:229], v[232:233]
	v_pk_add_f32 v[190:191], v[226:227], v[230:231]
	v_pk_add_f32 v[236:237], v[236:237], v[240:241]
	v_pk_add_f32 v[234:235], v[234:235], v[238:239]
	v_pk_add_f32 v[236:237], v[188:189], v[236:237]
	v_pk_add_f32 v[234:235], v[190:191], v[234:235]
	v_pk_fma_f32 v[74:75], v[224:225], v[236:237], v[74:75]
	v_pk_fma_f32 v[72:73], v[222:223], v[234:235], v[72:73]
	global_store_dwordx4 v177, v[72:75], s[0:1]
	global_load_dwordx4 v[96:99], v[150:151], off
	global_load_dwordx4 v[180:183], v178, s[44:45]
	global_load_dwordx4 v[184:187], v178, s[52:53]
	global_load_dwordx4 v[214:217], v178, s[38:39]
	global_load_dwordx4 v[218:221], v178, s[40:41]
	global_load_dwordx4 v[222:225], v[152:153], off
	global_load_dwordx4 v[226:229], v179, s[44:45]
	global_load_dwordx4 v[230:233], v179, s[52:53]
	global_load_dwordx4 v[234:237], v179, s[38:39]
	global_load_dwordx4 v[238:241], v179, s[40:41]
	s_waitcnt vmcnt(0)
	v_pk_add_f32 v[188:189], v[182:183], v[186:187]
	v_pk_add_f32 v[190:191], v[180:181], v[184:185]
	v_pk_add_f32 v[216:217], v[216:217], v[220:221]
	v_pk_add_f32 v[214:215], v[214:215], v[218:219]
	v_pk_add_f32 v[216:217], v[188:189], v[216:217]
	v_pk_add_f32 v[214:215], v[190:191], v[214:215]
	v_pk_fma_f32 v[70:71], v[98:99], v[216:217], v[70:71]
	v_pk_fma_f32 v[68:69], v[96:97], v[214:215], v[68:69]
	global_store_dwordx4 v178, v[68:71], s[0:1]
	v_pk_add_f32 v[188:189], v[228:229], v[232:233]
	v_pk_add_f32 v[190:191], v[226:227], v[230:231]
	v_pk_add_f32 v[236:237], v[236:237], v[240:241]
	v_pk_add_f32 v[234:235], v[234:235], v[238:239]
	v_pk_add_f32 v[236:237], v[188:189], v[236:237]
	v_pk_add_f32 v[234:235], v[190:191], v[234:235]
	v_pk_fma_f32 v[66:67], v[224:225], v[236:237], v[66:67]
	v_pk_fma_f32 v[64:65], v[222:223], v[234:235], v[64:65]
	global_store_dwordx4 v179, v[64:67], s[0:1]
